# GEMM prologue: all 14 stage loads of K-tiles 0/1 issued before the first wait (was 8 + 6 around a wait and barrier)
# speedup vs baseline: 1.0026x; 1.0026x over previous
; #define PG8_STAGE(bufoff, gbase, voff) do { _Pragma("unroll") for (int _i = 0; _i < 2; ++_i) \
;         __builtin_amdgcn_global_load_lds((const unsigned*)((const char*)(gbase) + (voff)[_i]), (PG8_LAS unsigned*)(lds + (bufoff) + ldsw + _i * 8192), 16, 0, 0); } while (0)
; #define PG8_WAIT_V(n) asm volatile("s_waitcnt vmcnt(" #n ")" ::: "memory")
; #define PG8_BAR __builtin_amdgcn_s_barrier()
; template <class Epi, class Sched, bool ALIGN_EPI = false, bool SP2 = false>
; __device__ __forceinline__ void gemm_phase(PG8_LAS unsigned char* lds, const Gemm g, const Sched& S, const Epi& E) {
;     ...
;     if constexpr (SP2) {
;         PG8_STAGE(PG8_SB(0, 0), cB, voffB); PG8_STAGE(PG8_SB(0, 1), cB + hstep, voffB); PG8_STAGE(PG8_SA(0, 0), cA, voffA); PG8_STAGE(PG8_SA(0, 1), cA + hstep, voffA);
;         if (wr == 1) PG8_BAR;
;         PG8_WAIT_V(2); PG8_BAR;
;         PG8_STAGE(PG8_SB(1, 0), cB + kstep, voffB); PG8_STAGE(PG8_SA(1, 0), cA + kstep, voffA); PG8_STAGE(PG8_SB(1, 1), cB + hstep + kstep, voffB);
;         PG8_WAIT_V(6); PG8_BAR;
.LBB0_803:
	s_lshl_b32 s58, s35, 6
	s_lshl_b32 s9, s35, 13
	s_lshl_b32 s35, s36, 5
	s_and_b32 s59, s35, 0x60
	s_lshl_b32 s35, s59, 7
	s_add_u32 s28, s4, s28
	s_addc_u32 s29, s5, s29
	s_add_u32 s30, s4, s30
	s_addc_u32 s31, s5, s31
	s_add_i32 m0, s54, 0x18000
	v_lshl_add_u64 v[6:7], v[6:7], 0, s[88:89]
	global_load_lds_dwordx4 v[6:7], off
	v_lshl_add_u64 v[4:5], v[4:5], 0, s[88:89]
	s_add_i32 m0, s54, 0x1a000
	s_add_i32 s60, s54, 0x8000
	s_add_i32 s61, s54, 0xa000
	global_load_lds_dwordx4 v[4:5], off
	v_lshl_add_u64 v[0:1], v[0:1], 0, s[88:89]
	s_mov_b32 m0, s60
	s_add_u32 s4, s6, 0x40080
	global_load_lds_dwordx4 v[0:1], off
	v_lshl_add_u64 v[0:1], v[2:3], 0, s[88:89]
	s_mov_b32 m0, s61
	s_addc_u32 s5, s7, 0
	global_load_lds_dwordx4 v[0:1], off
	s_add_i32 m0, s54, 0x1c000
	v_lshl_add_u64 v[0:1], s[4:5], 0, v[134:135]
	global_load_lds_dwordx4 v[0:1], off
	v_lshl_add_u64 v[0:1], s[4:5], 0, v[138:139]
	s_add_i32 m0, s54, 0x1e000
	s_movk_i32 s4, 0x3c0
	global_load_lds_dwordx4 v[0:1], off
	s_waitcnt vmcnt(8)
	s_barrier
	v_and_b32_e32 v0, 48, v8
	v_lshlrev_b32_e32 v1, 6, v8
	v_and_or_b32 v0, v1, s4, v0
	v_lshlrev_b32_e32 v1, 2, v8
	v_and_b32_e32 v1, 32, v1
	s_cmpk_lt_u32 s34, 0x100
	v_bitop3_b32 v172, s35, v0, v1 bitop3:0xf6
	s_cselect_b64 s[34:35], -1, 0
	s_lshl_b32 s66, s3, 3
	v_bitop3_b32 v2, v0, s9, v1 bitop3:0xde
	v_cvt_f32_ubyte0_e32 v0, s66
	v_rcp_iflag_f32_e32 v0, v0
	s_lshr_b32 s63, s86, 3
	s_ashr_i32 s3, s2, 31
	s_ashr_i32 s62, s52, 31
	v_mul_f32_e32 v0, 0x4f7ffffe, v0
	s_and_b32 s64, s86, 4
	s_add_i32 s65, s63, 1
	s_lshl_b64 s[4:5], s[2:3], 20
	v_cvt_u32_f32_e32 v0, v0
	s_add_u32 s67, s12, s4
	s_addc_u32 s68, s13, s5
	s_mul_hi_i32 s3, s2, 0x1f00000
	s_mul_i32 s2, s2, 0x1f00000
	s_add_u32 s69, s67, s2
	s_addc_u32 s70, s68, s3
	v_readfirstlane_b32 s3, v0
	v_lshlrev_b32_e32 v0, 14, v9
	v_and_b32_e32 v0, 0xffff8000, v0
	v_lshl_add_u32 v0, v10, 11, v0
	v_and_b32_e32 v1, 1, v9
	v_lshl_or_b32 v0, v1, 6, v0
	v_lshl_add_u32 v140, v11, 1, v0
	v_lshlrev_b32_e32 v0, 14, v12
	s_sub_i32 s2, 0, s66
	v_and_b32_e32 v0, 0xffff8000, v0
	s_waitcnt vmcnt(6)
	s_mul_i32 s2, s2, s3
	v_lshl_add_u32 v0, v13, 11, v0
	v_and_b32_e32 v1, 1, v12
	s_mul_hi_u32 s2, s3, s2
	v_lshl_or_b32 v0, v1, 6, v0
	s_mov_b32 s71, 0
	s_add_i32 s76, s3, s2
	v_mov_b32_e32 v141, v193
	v_lshl_add_u32 v142, v14, 1, v0
	v_mov_b32_e32 v143, v193
	v_add_u32_e32 v173, 0, v2
	v_mov_b64_e32 v[144:145], s[86:87]
	s_barrier
	s_branch .LBB0_806

; #define PG8_STAGE(bufoff, gbase, voff) do { _Pragma("unroll") for (int _i = 0; _i < 2; ++_i) \
;         __builtin_amdgcn_global_load_lds((const unsigned*)((const char*)(gbase) + (voff)[_i]), (PG8_LAS unsigned*)(lds + (bufoff) + ldsw + _i * 8192), 16, 0, 0); } while (0)
; #define PG8_WAIT_V(n) asm volatile("s_waitcnt vmcnt(" #n ")" ::: "memory")
; #define PG8_BAR __builtin_amdgcn_s_barrier()
; template <class Epi, class Sched, bool ALIGN_EPI = false, bool SP2 = false>
; __device__ __forceinline__ void gemm_phase(PG8_LAS unsigned char* lds, const Gemm g, const Sched& S, const Epi& E) {
;     ...
;     if constexpr (SP2) {
;         PG8_STAGE(PG8_SB(0, 0), cB, voffB); PG8_STAGE(PG8_SB(0, 1), cB + hstep, voffB); PG8_STAGE(PG8_SA(0, 0), cA, voffA); PG8_STAGE(PG8_SA(0, 1), cA + hstep, voffA);
;         if (wr == 1) PG8_BAR;
;         PG8_WAIT_V(2); PG8_BAR;
;         PG8_STAGE(PG8_SB(1, 0), cB + kstep, voffB); PG8_STAGE(PG8_SA(1, 0), cA + kstep, voffA); PG8_STAGE(PG8_SB(1, 1), cB + hstep + kstep, voffB);
;         PG8_WAIT_V(6); PG8_BAR;
.LBB0_1772:
	s_cmp_eq_u32 s2, 1
	s_cselect_b64 s[6:7], -1, 0
	s_and_b64 s[30:31], s[22:23], s[6:7]
	s_add_u32 s34, s26, 0x5000000
	s_addc_u32 s35, s27, 0
	s_add_u32 s36, s26, 0xc400000
	s_addc_u32 s37, s27, 0
	s_and_b32 s65, s5, 3
	s_lshr_b32 s66, s58, 6
	s_lshl_b32 s67, s4, 6
	s_lshl_b32 s2, s4, 13
	s_lshl_b32 s68, s65, 5
	s_lshl_b32 s4, s65, 12
	s_add_u32 s38, s26, 0x8000000
	s_addc_u32 s39, s27, 0
	s_add_i32 m0, s61, 0x18000
	v_lshl_add_u64 v[0:1], v[0:1], 0, s[88:89]
	global_load_lds_dwordx4 v[0:1], off
	v_lshl_add_u64 v[0:1], v[2:3], 0, s[88:89]
	s_add_i32 m0, s61, 0x1a000
	s_add_i32 s69, s61, 0x8000
	global_load_lds_dwordx4 v[0:1], off
	v_lshl_add_u64 v[0:1], v[8:9], 0, s[88:89]
	s_mov_b32 m0, s69
	s_add_i32 s70, s61, 0xa000
	global_load_lds_dwordx4 v[0:1], off
	v_lshl_add_u64 v[0:1], v[10:11], 0, s[88:89]
	s_mov_b32 m0, s70
	s_movk_i32 s5, 0x3c0
	global_load_lds_dwordx4 v[0:1], off
	s_add_i32 m0, s61, 0x1c000
	v_lshl_add_u64 v[0:1], v[4:5], 0, s[88:89]
	global_load_lds_dwordx4 v[0:1], off
	v_lshl_add_u64 v[0:1], v[6:7], 0, s[88:89]
	s_add_i32 m0, s61, 0x1e000
	s_add_i32 s71, s66, -2
	global_load_lds_dwordx4 v[0:1], off
	s_waitcnt vmcnt(8)
	s_barrier
	v_and_b32_e32 v0, 48, v12
	v_lshlrev_b32_e32 v1, 6, v12
	v_and_or_b32 v0, v1, s5, v0
	v_lshlrev_b32_e32 v1, 2, v12
	v_and_b32_e32 v1, 32, v1
	s_waitcnt vmcnt(6)
	v_bitop3_b32 v2, v0, s2, v1 bitop3:0xde
	s_cmpk_lt_u32 s3, 0x100
	v_readlane_b32 s2, v253, 55
	v_bitop3_b32 v240, v0, s4, v1 bitop3:0xde
	s_cselect_b64 s[40:41], -1, 0
	s_waitcnt vmcnt(0)
	v_cmp_ne_u64_e64 s[4:5], 0, v[194:195]
	v_lshl_add_u64 v[202:203], s[24:25], 0, v[200:201]
	v_lshl_add_u64 v[204:205], s[24:25], 0, v[198:199]
	s_mov_b32 s25, 0
	v_add_u32_e32 v241, 0, v2
	v_readlane_b32 s48, v253, 54
	s_mov_b32 s49, s2
	s_barrier
	v_readlane_b32 s3, v253, 56
	s_branch .LBB0_1775

; #define PG8_STAGE(bufoff, gbase, voff) do { _Pragma("unroll") for (int _i = 0; _i < 2; ++_i) \
;         __builtin_amdgcn_global_load_lds((const unsigned*)((const char*)(gbase) + (voff)[_i]), (PG8_LAS unsigned*)(lds + (bufoff) + ldsw + _i * 8192), 16, 0, 0); } while (0)
; #define PG8_WAIT_V(n) asm volatile("s_waitcnt vmcnt(" #n ")" ::: "memory")
; #define PG8_BAR __builtin_amdgcn_s_barrier()
; template <class Epi, class Sched, bool ALIGN_EPI = false, bool SP2 = false>
; __device__ __forceinline__ void gemm_phase(PG8_LAS unsigned char* lds, const Gemm g, const Sched& S, const Epi& E) {
;     ...
;     if constexpr (SP2) {
;         PG8_STAGE(PG8_SB(0, 0), cB, voffB); PG8_STAGE(PG8_SB(0, 1), cB + hstep, voffB); PG8_STAGE(PG8_SA(0, 0), cA, voffA); PG8_STAGE(PG8_SA(0, 1), cA + hstep, voffA);
;         if (wr == 1) PG8_BAR;
;         PG8_WAIT_V(2); PG8_BAR;
;         PG8_STAGE(PG8_SB(1, 0), cB + kstep, voffB); PG8_STAGE(PG8_SA(1, 0), cA + kstep, voffA); PG8_STAGE(PG8_SB(1, 1), cB + hstep + kstep, voffB);
;         PG8_WAIT_V(6); PG8_BAR;
.LBB0_1848:
	s_add_u32 s51, s26, 0x38800000
	s_addc_u32 s57, s27, 0
	s_add_i32 m0, s9, 0x18000
	v_lshl_add_u64 v[0:1], v[0:1], 0, s[88:89]
	global_load_lds_dwordx4 v[0:1], off
	v_lshl_add_u64 v[0:1], v[2:3], 0, s[88:89]
	s_add_i32 m0, s9, 0x1a000
	s_add_i32 s58, s9, 0x8000
	global_load_lds_dwordx4 v[0:1], off
	v_lshl_add_u64 v[0:1], v[8:9], 0, s[88:89]
	s_mov_b32 m0, s58
	s_add_i32 s59, s9, 0xa000
	global_load_lds_dwordx4 v[0:1], off
	v_lshl_add_u64 v[0:1], v[10:11], 0, s[88:89]
	s_mov_b32 m0, s59
	s_lshl_b32 s61, s6, 6
	global_load_lds_dwordx4 v[0:1], off
	s_add_i32 m0, s9, 0x1c000
	v_lshl_add_u64 v[0:1], v[4:5], 0, s[88:89]
	global_load_lds_dwordx4 v[0:1], off
	v_lshl_add_u64 v[0:1], v[6:7], 0, s[88:89]
	s_add_i32 m0, s9, 0x1e000
	s_lshl_b32 s3, s6, 13
	global_load_lds_dwordx4 v[0:1], off
	s_waitcnt vmcnt(8)
	s_barrier
	v_and_b32_e32 v0, 48, v12
	v_lshlrev_b32_e32 v1, 6, v12
	s_movk_i32 s6, 0x3c0
	v_and_or_b32 v0, v1, s6, v0
	v_lshlrev_b32_e32 v1, 2, v12
	v_and_b32_e32 v1, 32, v1
	v_bitop3_b32 v2, v0, s3, v1 bitop3:0xde
	s_lshl_b32 s3, s5, 5
	s_and_b32 s60, s3, 0x60
	s_lshl_b32 s3, s60, 7
	s_waitcnt vmcnt(6)
	s_cmpk_lt_u32 s4, 0x100
	v_readlane_b32 s28, v254, 14
	v_bitop3_b32 v134, s3, v0, v1 bitop3:0xf6
	s_cselect_b64 s[26:27], -1, 0
	s_addk_i32 s61, 0xc000
	v_add_u32_e32 v135, 0, v2
	v_readlane_b32 s29, v254, 15
	s_barrier
	s_waitcnt vmcnt(0)
	s_branch .LBB0_1851

; #define PG8_STAGE(bufoff, gbase, voff) do { _Pragma("unroll") for (int _i = 0; _i < 2; ++_i) \
;         __builtin_amdgcn_global_load_lds((const unsigned*)((const char*)(gbase) + (voff)[_i]), (PG8_LAS unsigned*)(lds + (bufoff) + ldsw + _i * 8192), 16, 0, 0); } while (0)
; #define PG8_WAIT_V(n) asm volatile("s_waitcnt vmcnt(" #n ")" ::: "memory")
; #define PG8_BAR __builtin_amdgcn_s_barrier()
; template <class Epi, class Sched, bool ALIGN_EPI = false, bool SP2 = false>
; __device__ __forceinline__ void gemm_phase(PG8_LAS unsigned char* lds, const Gemm g, const Sched& S, const Epi& E) {
;     ...
;     if constexpr (SP2) {
;         PG8_STAGE(PG8_SB(0, 0), cB, voffB); PG8_STAGE(PG8_SB(0, 1), cB + hstep, voffB); PG8_STAGE(PG8_SA(0, 0), cA, voffA); PG8_STAGE(PG8_SA(0, 1), cA + hstep, voffA);
;         if (wr == 1) PG8_BAR;
;         PG8_WAIT_V(2); PG8_BAR;
;         PG8_STAGE(PG8_SB(1, 0), cB + kstep, voffB); PG8_STAGE(PG8_SA(1, 0), cA + kstep, voffA); PG8_STAGE(PG8_SB(1, 1), cB + hstep + kstep, voffB);
;         PG8_WAIT_V(6); PG8_BAR;
.LBB0_2025:
	s_and_b64 s[10:11], s[14:15], exec
	s_mov_b32 s5, 0x2b000000
	s_cselect_b32 s5, s5, 0x30000000
	s_cselect_b32 s10, 0x3db504f3, 1.0
	s_add_u32 s12, s6, s5
	s_addc_u32 s13, s7, 0
	s_add_u32 s18, s6, 0xc710000
	s_addc_u32 s19, s7, 0
	s_lshl_b32 s51, s0, 6
	s_lshl_b32 s5, s0, 13
	s_lshl_b32 s0, s1, 5
	s_and_b32 s53, s0, 0x60
	s_add_i32 m0, s47, 0x18000
	v_lshl_add_u64 v[6:7], v[6:7], 0, s[88:89]
	s_lshl_b32 s25, s53, 7
	global_load_lds_dwordx4 v[6:7], off
	v_lshl_add_u64 v[4:5], v[4:5], 0, s[88:89]
	s_add_i32 m0, s47, 0x1a000
	s_add_i32 s54, s47, 0x8000
	s_add_i32 s55, s47, 0xa000
	global_load_lds_dwordx4 v[4:5], off
	v_lshl_add_u64 v[0:1], v[0:1], 0, s[88:89]
	s_mov_b32 m0, s54
	s_add_u32 s0, s38, 0x40080
	global_load_lds_dwordx4 v[0:1], off
	v_lshl_add_u64 v[0:1], v[2:3], 0, s[88:89]
	s_mov_b32 m0, s55
	s_addc_u32 s1, s39, 0
	global_load_lds_dwordx4 v[0:1], off
	s_add_i32 m0, s47, 0x1c000
	v_lshl_add_u64 v[0:1], s[0:1], 0, v[192:193]
	global_load_lds_dwordx4 v[0:1], off
	v_lshl_add_u64 v[0:1], s[0:1], 0, v[132:133]
	s_add_i32 m0, s47, 0x1e000
	s_cmpk_lt_u32 s22, 0x100
	global_load_lds_dwordx4 v[0:1], off
	s_waitcnt vmcnt(8)
	s_barrier
	s_cselect_b64 s[22:23], -1, 0
	s_lshr_b32 s57, s86, 3
	v_and_b32_e32 v0, 48, v8
	v_lshlrev_b32_e32 v1, 6, v8
	s_movk_i32 s0, 0x3c0
	s_and_b32 s58, s86, 4
	s_or_b32 s59, s57, 1
	s_lshr_b32 s60, s24, 5
	v_and_or_b32 v0, v1, s0, v0
	s_and_b64 s[0:1], s[14:15], exec
	s_cselect_b32 s61, 9, 12
	s_abs_i32 s62, s60
	v_cvt_f32_u32_e32 v1, s62
	v_lshlrev_b32_e32 v2, 2, v8
	v_and_b32_e32 v2, 32, v2
	v_bitop3_b32 v3, v0, s5, v2 bitop3:0xde
	v_rcp_iflag_f32_e32 v1, v1
	v_bitop3_b32 v167, s25, v0, v2 bitop3:0xf6
	s_sub_i32 s0, 0, s62
	s_waitcnt vmcnt(6)
	v_mul_f32_e32 v0, 0x4f7ffffe, v1
	v_cvt_u32_f32_e32 v0, v0
	v_and_b32_e32 v1, 1, v9
	s_mov_b32 s56, 0
	s_mov_b32 s11, s10
	v_readfirstlane_b32 s1, v0
	v_lshlrev_b32_e32 v0, 14, v9
	v_and_b32_e32 v0, 0xffff8000, v0
	v_lshl_add_u32 v0, v10, 11, v0
	v_lshl_or_b32 v0, v1, 6, v0
	v_lshl_add_u32 v134, v11, 1, v0
	v_lshlrev_b32_e32 v0, 14, v12
	v_and_b32_e32 v0, 0xffff8000, v0
	s_mul_i32 s0, s0, s1
	v_lshl_add_u32 v0, v13, 11, v0
	v_and_b32_e32 v1, 1, v12
	s_mul_hi_u32 s0, s1, s0
	v_lshl_or_b32 v0, v1, 6, v0
	s_mov_b32 s20, s10
	s_mov_b32 s21, s10
	s_ashr_i32 s63, s60, 31
	s_add_i32 s64, s1, s0
	v_mov_b32_e32 v135, v193
	v_lshl_add_u32 v136, v14, 1, v0
	v_mov_b32_e32 v137, v193
	v_add_u32_e32 v168, 0, v3
	s_barrier
	s_branch .LBB0_2028
